# loop-edge edit: ring rotation and pointer advance moved in front of the loop-back barrier; softmax max/sum chain shortened by 5 redundant VALU per tile
# speedup vs baseline: 1.0193x; 1.0020x over previous
; template <bool WIN>
; __device__ __forceinline__ void partialSM(f32x16& p0, f32x16& p1, float& m_reg, float& mn, float& alpha) {
;   constexpr float C = SCALE * 1.4426950408889634f;
;   float pmax = p0[0];
; #pragma unroll
;   for (int r = 1; r < 16; ++r) pmax = fmaxf(pmax, p0[r]);
; #pragma unroll
;   for (int r = 0; r < 16; ++r) pmax = fmaxf(pmax, p1[r]);
;   { auto rr = __builtin_amdgcn_permlane32_swap(__float_as_uint(pmax), __float_as_uint(pmax), false, false);
;     pmax = fmaxf(__uint_as_float(rr[0]), __uint_as_float(rr[1])); }
;   if (__builtin_expect(__all(pmax - m_reg <= THR / SCALE), 1)) { mn = m_reg; alpha = 1.f; }
;   else { mn = fmaxf(m_reg, pmax); alpha = __builtin_amdgcn_exp2f((m_reg - mn) * C); m_reg = mn; }
;   float mnC = -mn * C;
; #pragma unroll
;   for (int r = 0; r < 16; ++r) p0[r] = fmaf(p0[r], C, mnC);
; #pragma unroll
;   for (int r = 0; r < 16; ++r) p1[r] = fmaf(p1[r], C, mnC);
; template <bool WIN>
; __device__ __forceinline__ void qkt(f32x16& p0, f32x16& p1, const bf16_t* Ks, const bf16x8* qr, int r32, int hi, int dq) {
;   p0 = f32x16{}; p1 = f32x16{};
;   if (WIN) {
;     const int t = 4 * hi - dq + 128;
; #pragma unroll
;     for (int r = 0; r < 16; ++r) { const unsigned d0 = (unsigned)(t + (r & 3) + 8 * (r >> 2)), d1 = d0 + 32u;
;       p0[r] = d0 > 256u ? -1e30f : 0.f; p1[r] = d1 > 256u ? -1e30f : 0.f; }
;   }
; #pragma unroll
;   for (int d0 = 0; d0 < 8; ++d0) { int cb = (d0 * 16 + hi * 8) * 2;
;     bf16x8 b0 = *reinterpret_cast<const bf16x8*>((const char*)Ks + KSWZ(r32, cb));
;     bf16x8 b1 = *reinterpret_cast<const bf16x8*>((const char*)Ks + KSWZ(32 + r32, cb));
;     p0 = __builtin_amdgcn_mfma_f32_32x32x16_bf16(b0, qr[d0], p0, 0, 0, 0);
;     p1 = __builtin_amdgcn_mfma_f32_32x32x16_bf16(b1, qr[d0], p1, 0, 0, 0); }
.LBB0_643:
	s_and_b32 s69, s68, 1
	s_xor_b32 s33, s69, 1
	s_lshl_b32 s0, s33, 14
	s_add_i32 s0, s35, s0
	v_lshl_add_u64 v[254:255], s[22:23], 0, v[206:207]
	s_mov_b32 m0, s0
	s_nop 0
	global_load_lds_dwordx4 v[254:255], off
	v_lshl_add_u64 v[254:255], s[22:23], 0, v[204:205]
	s_add_i32 m0, s0, 0x400
	s_nop 0
	global_load_lds_dwordx4 v[254:255], off
	s_setprio 1
	s_lshl_b32 s0, s69, 14
	s_add_i32 s0, s0, 0
	v_add3_u32 v0, s0, v209, v199
	ds_read_b128 v[130:133], v0
	ds_read_b128 v[134:137], v0 offset:8192
	v_add3_u32 v0, s0, v210, v199
	ds_read_b128 v[232:235], v0
	ds_read_b128 v[236:239], v0 offset:8192
	v_add3_u32 v0, s0, v211, v199
	ds_read_b128 v[246:249], v0
	ds_read_b128 v[250:253], v0 offset:8192
	s_waitcnt lgkmcnt(4)
	v_mfma_f32_32x32x16_bf16 v[146:161], v[130:133], v[162:165], 0
	v_mfma_f32_32x32x16_bf16 v[130:145], v[134:137], v[162:165], 0
	s_waitcnt lgkmcnt(2)
	v_mfma_f32_32x32x16_bf16 v[146:161], v[232:235], v[166:169], v[146:161]
	v_mfma_f32_32x32x16_bf16 v[130:145], v[236:239], v[166:169], v[130:145]
	v_add3_u32 v0, s0, v212, v199
	ds_read_b128 v[232:235], v0
	ds_read_b128 v[236:239], v0 offset:8192
	s_waitcnt lgkmcnt(2)
	v_mfma_f32_32x32x16_bf16 v[146:161], v[246:249], v[170:173], v[146:161]
	v_mfma_f32_32x32x16_bf16 v[130:145], v[250:253], v[170:173], v[130:145]
	v_add3_u32 v0, s0, v213, v199
	ds_read_b128 v[246:249], v0
	ds_read_b128 v[250:253], v0 offset:8192
	s_waitcnt lgkmcnt(2)
	v_mfma_f32_32x32x16_bf16 v[146:161], v[232:235], v[174:177], v[146:161]
	v_mfma_f32_32x32x16_bf16 v[130:145], v[236:239], v[174:177], v[130:145]
	v_add3_u32 v0, s0, v214, v199
	ds_read_b128 v[232:235], v0
	ds_read_b128 v[236:239], v0 offset:8192
	s_waitcnt lgkmcnt(2)
	v_mfma_f32_32x32x16_bf16 v[146:161], v[246:249], v[178:181], v[146:161]
	v_mfma_f32_32x32x16_bf16 v[130:145], v[250:253], v[178:181], v[130:145]
	v_add3_u32 v0, s0, v215, v199
	ds_read_b128 v[246:249], v0
	ds_read_b128 v[250:253], v0 offset:8192
	s_waitcnt lgkmcnt(2)
	v_mfma_f32_32x32x16_bf16 v[146:161], v[232:235], v[182:185], v[146:161]
	v_mfma_f32_32x32x16_bf16 v[130:145], v[236:239], v[182:185], v[130:145]
	v_add3_u32 v0, s0, v216, v199
	ds_read_b128 v[232:235], v0
	ds_read_b128 v[236:239], v0 offset:8192
	s_waitcnt lgkmcnt(2)
	v_mfma_f32_32x32x16_bf16 v[146:161], v[246:249], v[186:189], v[146:161]
	v_mfma_f32_32x32x16_bf16 v[130:145], v[250:253], v[186:189], v[130:145]
	s_waitcnt lgkmcnt(0)
	v_mfma_f32_32x32x16_bf16 v[146:161], v[232:235], v[190:193], v[146:161]
	v_mfma_f32_32x32x16_bf16 v[130:145], v[236:239], v[190:193], v[130:145]
	s_setprio 0
	s_nop 7
	s_nop 3
	v_max_f32_e32 v0, v146, v147
	v_max3_f32 v0, v0, v148, v149
	v_max3_f32 v0, v0, v150, v151
	v_max3_f32 v0, v0, v152, v153
	v_max3_f32 v0, v0, v154, v155
	v_max3_f32 v0, v0, v156, v157
	v_max3_f32 v0, v0, v158, v159
	v_max3_f32 v0, v0, v160, v161
	v_max3_f32 v0, v0, v130, v131
	v_max3_f32 v0, v0, v132, v133
	v_max3_f32 v0, v0, v134, v135
	v_max3_f32 v0, v0, v136, v137
	v_max3_f32 v0, v0, v138, v139
	v_max3_f32 v0, v0, v140, v141
	v_max3_f32 v0, v0, v142, v143
	v_max3_f32 v0, v0, v144, v145
	v_mov_b32_e32 v231, v0
	s_nop 1
	v_permlane32_swap_b32_e32 v0, v231
	v_max_f32_e32 v0, v0, v231
	v_sub_f32_e32 v231, v0, v229
	s_mov_b32 s0, 0x42b504f3
	v_cmp_ge_f32_e32 vcc, s0, v231
	v_max_f32_e32 v232, v229, v229
	s_cmp_eq_u64 vcc, exec
	v_max_f32_e32 v232, v232, v0
	s_cselect_b64 vcc, -1, 0
	v_sub_f32_e32 v0, v229, v232
	v_cndmask_b32_e32 v229, v232, v229, vcc
	v_mul_f32_e32 v231, 0xbe0293ee, v229
	v_fmamk_f32 v146, v146, 0x3e0293ee, v231
	v_fmamk_f32 v147, v147, 0x3e0293ee, v231
	v_fmamk_f32 v148, v148, 0x3e0293ee, v231
	v_fmamk_f32 v149, v149, 0x3e0293ee, v231
	v_fmamk_f32 v150, v150, 0x3e0293ee, v231
	v_fmamk_f32 v151, v151, 0x3e0293ee, v231
	v_fmamk_f32 v152, v152, 0x3e0293ee, v231
	v_fmamk_f32 v153, v153, 0x3e0293ee, v231
	v_fmamk_f32 v154, v154, 0x3e0293ee, v231
	v_fmamk_f32 v155, v155, 0x3e0293ee, v231
	v_fmamk_f32 v156, v156, 0x3e0293ee, v231
	v_fmamk_f32 v157, v157, 0x3e0293ee, v231
	v_fmamk_f32 v158, v158, 0x3e0293ee, v231
	v_fmamk_f32 v159, v159, 0x3e0293ee, v231
	v_fmamk_f32 v160, v160, 0x3e0293ee, v231
	v_fmamk_f32 v161, v161, 0x3e0293ee, v231
	v_fmamk_f32 v130, v130, 0x3e0293ee, v231
	v_fmamk_f32 v131, v131, 0x3e0293ee, v231
	v_fmamk_f32 v132, v132, 0x3e0293ee, v231
	v_fmamk_f32 v133, v133, 0x3e0293ee, v231
	v_fmamk_f32 v134, v134, 0x3e0293ee, v231
	v_fmamk_f32 v135, v135, 0x3e0293ee, v231
	v_fmamk_f32 v136, v136, 0x3e0293ee, v231
	v_fmamk_f32 v137, v137, 0x3e0293ee, v231
	v_fmamk_f32 v138, v138, 0x3e0293ee, v231
	v_fmamk_f32 v139, v139, 0x3e0293ee, v231
	v_fmamk_f32 v140, v140, 0x3e0293ee, v231
	v_fmamk_f32 v141, v141, 0x3e0293ee, v231
	v_fmamk_f32 v142, v142, 0x3e0293ee, v231
	v_fmamk_f32 v143, v143, 0x3e0293ee, v231
	v_fmamk_f32 v144, v144, 0x3e0293ee, v231
	v_fmac_f32_e32 v231, 0x3e0293ee, v145
	v_exp_f32_e32 v145, v146
	v_exp_f32_e32 v146, v147
	v_exp_f32_e32 v147, v148
	v_exp_f32_e32 v148, v149
	v_exp_f32_e32 v149, v150
	v_exp_f32_e32 v150, v151
	v_exp_f32_e32 v151, v152
	v_exp_f32_e32 v152, v153
	v_exp_f32_e32 v153, v154
	v_exp_f32_e32 v154, v155
	v_exp_f32_e32 v155, v156
	v_exp_f32_e32 v156, v157
	v_exp_f32_e32 v157, v158
	v_exp_f32_e32 v158, v159
	v_exp_f32_e32 v159, v160
	v_exp_f32_e32 v160, v161
	v_exp_f32_e32 v161, v134
	v_add_f32_e32 v134, v146, v145
	v_add_f32_e32 v134, v147, v134
	v_add_f32_e32 v134, v148, v134
	v_add_f32_e32 v134, v149, v134
	v_add_f32_e32 v134, v150, v134
	v_add_f32_e32 v134, v151, v134
	v_add_f32_e32 v134, v152, v134
	v_add_f32_e32 v134, v153, v134
	v_add_f32_e32 v134, v154, v134
	v_add_f32_e32 v134, v155, v134
	v_add_f32_e32 v134, v156, v134
	v_exp_f32_e32 v130, v130
; __device__ __forceinline__ void finishSM(f32x16& p0, f32x16& p1, float alpha, float& l_reg, bf16x8& pa0, bf16x8& pa1, bf16x8& pa2, bf16x8& pa3) {
; #pragma unroll
;   for (int r = 0; r < 16; ++r) p1[r] = __builtin_amdgcn_exp2f(p1[r]);
;   float ps = 0;
; #pragma unroll
;   for (int r = 0; r < 16; ++r) ps += p0[r];
; #pragma unroll
;   for (int r = 0; r < 16; ++r) ps += p1[r];
;   { auto rr = __builtin_amdgcn_permlane32_swap(__float_as_uint(ps), __float_as_uint(ps), false, false);
;     ps = __uint_as_float(rr[0]) + __uint_as_float(rr[1]); }
;   l_reg = l_reg * alpha + ps;
;     ...
;   PK4(p0, 0, pa0); PK4(p0, 8, pa1); PK4(p1, 0, pa2); PK4(p1, 8, pa3);
	v_add_f32_e32 v134, v157, v134
	v_exp_f32_e32 v131, v131
	v_add_f32_e32 v134, v158, v134
	v_exp_f32_e32 v132, v132
	v_add_f32_e32 v134, v159, v134
	v_exp_f32_e32 v133, v133
	v_add_f32_e32 v134, v160, v134
	v_add_f32_e32 v134, v130, v134
	v_exp_f32_e32 v233, v135
	v_add_f32_e32 v134, v131, v134
	v_exp_f32_e32 v234, v136
	v_add_f32_e32 v134, v132, v134
	v_exp_f32_e32 v235, v137
	v_add_f32_e32 v134, v133, v134
	v_exp_f32_e32 v138, v138
	v_add_f32_e32 v134, v161, v134
	v_exp_f32_e32 v139, v139
	v_add_f32_e32 v134, v233, v134
	v_exp_f32_e32 v140, v140
	v_add_f32_e32 v134, v234, v134
	v_exp_f32_e32 v141, v141
	v_add_f32_e32 v134, v235, v134
	v_exp_f32_e32 v236, v142
	v_add_f32_e32 v134, v138, v134
	v_exp_f32_e32 v237, v143
	v_add_f32_e32 v134, v139, v134
	v_exp_f32_e32 v238, v144
	v_add_f32_e32 v134, v140, v134
	v_mul_f32_e32 v0, 0x3e0293ee, v0
	v_exp_f32_e32 v239, v231
	v_add_f32_e32 v134, v141, v134
	v_exp_f32_e32 v0, v0
	v_add_f32_e32 v134, v236, v134
	v_add_f32_e32 v134, v237, v134
	v_add_f32_e32 v134, v238, v134
	v_add_f32_e32 v231, v239, v134
	v_cndmask_b32_e64 v0, v0, 1.0, vcc
	v_mov_b32_e32 v232, v231
	v_cvt_pk_bf16_f32 v134, v145, v146
	v_cvt_pk_bf16_f32 v135, v147, v148
	v_cvt_pk_bf16_f32 v136, v149, v150
	v_cvt_pk_bf16_f32 v137, v151, v152
	v_cvt_pk_bf16_f32 v142, v153, v154
	v_cvt_pk_bf16_f32 v143, v155, v156
	v_cvt_pk_bf16_f32 v144, v157, v158
	v_cvt_pk_bf16_f32 v145, v159, v160
	v_cvt_pk_bf16_f32 v130, v130, v131
	v_cvt_pk_bf16_f32 v131, v132, v133
	v_cvt_pk_bf16_f32 v132, v161, v233
	v_cvt_pk_bf16_f32 v133, v234, v235
	v_cvt_pk_bf16_f32 v138, v138, v139
	v_cvt_pk_bf16_f32 v139, v140, v141
	v_cvt_pk_bf16_f32 v140, v236, v237
	v_cvt_pk_bf16_f32 v141, v238, v239
	v_permlane32_swap_b32_e32 v231, v232
	v_permlane32_swap_b32_e32 v134, v136
	v_permlane32_swap_b32_e32 v135, v137
	v_permlane32_swap_b32_e32 v142, v144
	v_permlane32_swap_b32_e32 v143, v145
	v_permlane32_swap_b32_e32 v130, v132
	v_permlane32_swap_b32_e32 v131, v133
	v_permlane32_swap_b32_e32 v138, v140
	v_permlane32_swap_b32_e32 v139, v141
	v_cmp_gt_f32_e32 vcc, 1.0, v0
	s_cbranch_vccz .LBB0_649
	s_and_saveexec_b64 s[0:1], s[6:7]
	ds_write_b32 v228, v0 offset:128
	s_or_b64 exec, exec, s[0:1]
	s_waitcnt lgkmcnt(0)
	v_add_u32_e32 v146, s67, v223
	ds_read_b128 v[158:161], v146 offset:224
	ds_read_b128 v[154:157], v146 offset:192
	ds_read_b128 v[150:153], v146 offset:160
	ds_read_b128 v[146:149], v146 offset:128
	s_waitcnt lgkmcnt(0)
	v_pk_mul_f32 v[126:127], v[126:127], v[158:159]
	v_pk_mul_f32 v[122:123], v[122:123], v[154:155]
	v_pk_mul_f32 v[118:119], v[118:119], v[150:151]
	v_pk_mul_f32 v[128:129], v[128:129], v[160:161]
	v_pk_mul_f32 v[124:125], v[124:125], v[156:157]
	v_pk_mul_f32 v[120:121], v[120:121], v[152:153]
	v_pk_mul_f32 v[116:117], v[116:117], v[148:149]
	v_pk_mul_f32 v[114:115], v[114:115], v[146:147]
	v_pk_mul_f32 v[110:111], v[110:111], v[158:159]
	v_pk_mul_f32 v[106:107], v[106:107], v[154:155]
	v_pk_mul_f32 v[102:103], v[102:103], v[150:151]
	v_pk_mul_f32 v[112:113], v[112:113], v[160:161]
	v_pk_mul_f32 v[108:109], v[108:109], v[156:157]
	v_pk_mul_f32 v[104:105], v[104:105], v[152:153]
	v_pk_mul_f32 v[100:101], v[100:101], v[148:149]
	v_pk_mul_f32 v[98:99], v[98:99], v[146:147]
	v_pk_mul_f32 v[94:95], v[94:95], v[158:159]
	v_pk_mul_f32 v[90:91], v[90:91], v[154:155]
	v_pk_mul_f32 v[86:87], v[86:87], v[150:151]
	v_pk_mul_f32 v[96:97], v[96:97], v[160:161]
	v_pk_mul_f32 v[92:93], v[92:93], v[156:157]
	v_pk_mul_f32 v[88:89], v[88:89], v[152:153]
	v_pk_mul_f32 v[84:85], v[84:85], v[148:149]
	v_pk_mul_f32 v[82:83], v[82:83], v[146:147]
	v_pk_mul_f32 v[78:79], v[78:79], v[158:159]
	v_pk_mul_f32 v[74:75], v[74:75], v[154:155]
	v_pk_mul_f32 v[70:71], v[70:71], v[150:151]
	v_pk_mul_f32 v[80:81], v[80:81], v[160:161]
	v_pk_mul_f32 v[76:77], v[76:77], v[156:157]
	v_pk_mul_f32 v[72:73], v[72:73], v[152:153]
	v_pk_mul_f32 v[68:69], v[68:69], v[148:149]
	v_pk_mul_f32 v[66:67], v[66:67], v[146:147]
	v_pk_mul_f32 v[62:63], v[62:63], v[158:159]
	v_pk_mul_f32 v[58:59], v[58:59], v[154:155]
	v_pk_mul_f32 v[54:55], v[54:55], v[150:151]
	v_pk_mul_f32 v[64:65], v[64:65], v[160:161]
	v_pk_mul_f32 v[60:61], v[60:61], v[156:157]
	v_pk_mul_f32 v[56:57], v[56:57], v[152:153]
	v_pk_mul_f32 v[52:53], v[52:53], v[148:149]
	v_pk_mul_f32 v[50:51], v[50:51], v[146:147]
	v_pk_mul_f32 v[46:47], v[46:47], v[158:159]
	v_pk_mul_f32 v[42:43], v[42:43], v[154:155]
	v_pk_mul_f32 v[38:39], v[38:39], v[150:151]
	v_pk_mul_f32 v[48:49], v[48:49], v[160:161]
	v_pk_mul_f32 v[44:45], v[44:45], v[156:157]
	v_pk_mul_f32 v[40:41], v[40:41], v[152:153]
	v_pk_mul_f32 v[36:37], v[36:37], v[148:149]
	v_pk_mul_f32 v[34:35], v[34:35], v[146:147]
	v_pk_mul_f32 v[30:31], v[30:31], v[158:159]
	v_pk_mul_f32 v[26:27], v[26:27], v[154:155]
	v_pk_mul_f32 v[22:23], v[22:23], v[150:151]
	v_pk_mul_f32 v[32:33], v[32:33], v[160:161]
	v_pk_mul_f32 v[28:29], v[28:29], v[156:157]
	v_pk_mul_f32 v[24:25], v[24:25], v[152:153]
	v_pk_mul_f32 v[20:21], v[20:21], v[148:149]
	v_pk_mul_f32 v[18:19], v[18:19], v[146:147]
	v_pk_mul_f32 v[14:15], v[14:15], v[158:159]
	v_pk_mul_f32 v[10:11], v[10:11], v[154:155]
	v_pk_mul_f32 v[6:7], v[6:7], v[150:151]
	v_pk_mul_f32 v[16:17], v[16:17], v[160:161]
	v_pk_mul_f32 v[12:13], v[12:13], v[156:157]
	v_pk_mul_f32 v[8:9], v[8:9], v[152:153]
	v_pk_mul_f32 v[4:5], v[4:5], v[148:149]
	v_pk_mul_f32 v[2:3], v[2:3], v[146:147]
; #define SBAR() __builtin_amdgcn_sched_barrier(0)
; template <int D0> __device__ __forceinline__ void pv_one(f32x16& od, int vb, bf16x8 pa0, bf16x8 pa1, bf16x8 pa2, bf16x8 pa3) {
;   const s16x4 l0 = tr_read<v_rd_off(D0, 0, 0)>(vb), h0 = tr_read<v_rd_off(D0, 0, 1)>(vb), l1 = tr_read<v_rd_off(D0, 1, 0)>(vb), h1 = tr_read<v_rd_off(D0, 1, 1)>(vb);
;   const s16x4 l2 = tr_read<v_rd_off(D0, 2, 0)>(vb), h2 = tr_read<v_rd_off(D0, 2, 1)>(vb), l3 = tr_read<v_rd_off(D0, 3, 0)>(vb), h3 = tr_read<v_rd_off(D0, 3, 1)>(vb);
;   asm volatile("s_waitcnt lgkmcnt(0)" ::: "memory"); SBAR();
;     ...
;   od = __builtin_amdgcn_mfma_f32_32x32x16_bf16(pa0, PK(l0, h0), od, 0, 0, 0);
;   od = __builtin_amdgcn_mfma_f32_32x32x16_bf16(pa1, PK(l1, h1), od, 0, 0, 0);
;   od = __builtin_amdgcn_mfma_f32_32x32x16_bf16(pa2, PK(l2, h2), od, 0, 0, 0);
;   od = __builtin_amdgcn_mfma_f32_32x32x16_bf16(pa3, PK(l3, h3), od, 0, 0, 0);
;     ...
; }
; __device__ __forceinline__ void pv_d0(f32x16* o, int vb, bf16x8 pa0, bf16x8 pa1, bf16x8 pa2, bf16x8 pa3) {
;   pv_one<0>(o[0], vb, pa0, pa1, pa2, pa3); pv_one<1>(o[1], vb, pa0, pa1, pa2, pa3); pv_one<2>(o[2], vb, pa0, pa1, pa2, pa3); pv_one<3>(o[3], vb, pa0, pa1, pa2, pa3);
; }
; template <int LDO>
; __device__ __forceinline__ void attn_unit_dv(const bf16_t* __restrict__ Qb, const bf16_t* __restrict__ Kh, const bf16_t* __restrict__ Vh, bf16_t* __restrict__ Ob, int NT, char* lds, LAS3 unsigned char* ldsl) {
;     ...
;     pv_d0(o, vb0 + buf * 32768, pa0, pa1, pa2, pa3);
;     pv_d0(o + 4, vb0 + buf * 32768 + 16384, pa0, pa1, pa2, pa3);
;     asm volatile("s_waitcnt vmcnt(0) lgkmcnt(0)" ::: "memory"); __builtin_amdgcn_s_barrier(); asm volatile("" ::: "memory");
.LBB0_649:
	s_waitcnt vmcnt(6)
	s_barrier
	s_lshl_b32 s0, s101, 15
	s_add_i32 s33, s66, s0
	v_lshl_add_u64 v[254:255], s[22:23], 0, v[202:203]
	s_mov_b64 s[0:1], 0x33e10000
	v_lshl_add_u64 v[254:255], v[254:255], 0, s[0:1]
	s_add_i32 m0, s33, 0x8000
	s_mov_b64 s[0:1], 0x80
	global_load_lds_dwordx4 v[254:255], off
	v_lshl_add_u64 v[254:255], v[254:255], 0, s[0:1]
	s_add_i32 m0, s33, 0x8400
	s_mov_b64 s[0:1], 0x780
	global_load_lds_dwordx4 v[254:255], off
	v_lshl_add_u64 v[254:255], v[254:255], 0, s[0:1]
	s_add_i32 m0, s33, 0x8800
	s_mov_b64 s[0:1], 0x80
	global_load_lds_dwordx4 v[254:255], off
	v_lshl_add_u64 v[254:255], v[254:255], 0, s[0:1]
	s_add_i32 m0, s33, 0x8c00
	s_nop 0
	global_load_lds_dwordx4 v[254:255], off
	v_add_f32_e32 v146, v231, v232
	v_fmac_f32_e32 v146, v230, v0
	s_add_i32 s68, s68, 1
	v_lshl_add_u32 v0, s98, 15, v224
	ds_read_b64_tr_b16 v[148:149], v0 offset:0
	ds_read_b64_tr_b16 v[150:151], v0 offset:0x800
	ds_read_b64_tr_b16 v[152:153], v0 offset:0x1000
	ds_read_b64_tr_b16 v[154:155], v0 offset:0x1800
	ds_read_b64_tr_b16 v[156:157], v0 offset:0x2000
	ds_read_b64_tr_b16 v[158:159], v0 offset:0x2800
	ds_read_b64_tr_b16 v[230:231], v0 offset:0x3000
	ds_read_b64_tr_b16 v[232:233], v0 offset:0x3800
	s_waitcnt lgkmcnt(0)
	s_nop 0
	v_mfma_f32_32x32x16_bf16 v[114:129], v[134:137], v[148:151], v[114:129]
	ds_read_b64_tr_b16 v[148:149], v0 offset:0x200
	ds_read_b64_tr_b16 v[150:151], v0 offset:0xa00
	v_mfma_f32_32x32x16_bf16 v[114:129], v[142:145], v[152:155], v[114:129]
	ds_read_b64_tr_b16 v[152:153], v0 offset:0x1200
	ds_read_b64_tr_b16 v[154:155], v0 offset:0x1a00
	v_mfma_f32_32x32x16_bf16 v[114:129], v[130:133], v[156:159], v[114:129]
	ds_read_b64_tr_b16 v[156:157], v0 offset:0x2200
	ds_read_b64_tr_b16 v[158:159], v0 offset:0x2a00
	ds_read_b64_tr_b16 v[234:235], v0 offset:0x3200
	ds_read_b64_tr_b16 v[236:237], v0 offset:0x3a00
	s_waitcnt lgkmcnt(0)
	v_mfma_f32_32x32x16_bf16 v[114:129], v[138:141], v[230:233], v[114:129]
	v_mfma_f32_32x32x16_bf16 v[98:113], v[134:137], v[148:151], v[98:113]
	ds_read_b64_tr_b16 v[148:149], v0 offset:0x400
	ds_read_b64_tr_b16 v[150:151], v0 offset:0xc00
	v_mfma_f32_32x32x16_bf16 v[98:113], v[142:145], v[152:155], v[98:113]
	ds_read_b64_tr_b16 v[152:153], v0 offset:0x1400
	ds_read_b64_tr_b16 v[154:155], v0 offset:0x1c00
	v_mfma_f32_32x32x16_bf16 v[98:113], v[130:133], v[156:159], v[98:113]
	ds_read_b64_tr_b16 v[156:157], v0 offset:0x2400
	ds_read_b64_tr_b16 v[158:159], v0 offset:0x2c00
	ds_read_b64_tr_b16 v[230:231], v0 offset:0x3400
	ds_read_b64_tr_b16 v[232:233], v0 offset:0x3c00
	s_waitcnt lgkmcnt(0)
	v_mfma_f32_32x32x16_bf16 v[98:113], v[138:141], v[234:237], v[98:113]
	v_mfma_f32_32x32x16_bf16 v[82:97], v[134:137], v[148:151], v[82:97]
	ds_read_b64_tr_b16 v[148:149], v0 offset:0x600
	ds_read_b64_tr_b16 v[150:151], v0 offset:0xe00
	v_mfma_f32_32x32x16_bf16 v[82:97], v[142:145], v[152:155], v[82:97]
	ds_read_b64_tr_b16 v[152:153], v0 offset:0x1600
	ds_read_b64_tr_b16 v[154:155], v0 offset:0x1e00
	v_mfma_f32_32x32x16_bf16 v[82:97], v[130:133], v[156:159], v[82:97]
	ds_read_b64_tr_b16 v[156:157], v0 offset:0x2600
	ds_read_b64_tr_b16 v[158:159], v0 offset:0x2e00
	ds_read_b64_tr_b16 v[234:235], v0 offset:0x3600
	ds_read_b64_tr_b16 v[236:237], v0 offset:0x3e00
	s_waitcnt lgkmcnt(0)
	v_mfma_f32_32x32x16_bf16 v[82:97], v[138:141], v[230:233], v[82:97]
	v_mfma_f32_32x32x16_bf16 v[66:81], v[134:137], v[148:151], v[66:81]
	v_add_u32_e32 v0, 0x4000, v0
	ds_read_b64_tr_b16 v[148:149], v0 offset:0
	ds_read_b64_tr_b16 v[150:151], v0 offset:0x800
	v_mfma_f32_32x32x16_bf16 v[66:81], v[142:145], v[152:155], v[66:81]
	ds_read_b64_tr_b16 v[152:153], v0 offset:0x1000
	ds_read_b64_tr_b16 v[154:155], v0 offset:0x1800
	v_mfma_f32_32x32x16_bf16 v[66:81], v[130:133], v[156:159], v[66:81]
	ds_read_b64_tr_b16 v[156:157], v0 offset:0x2000
	ds_read_b64_tr_b16 v[158:159], v0 offset:0x2800
	ds_read_b64_tr_b16 v[230:231], v0 offset:0x3000
	ds_read_b64_tr_b16 v[232:233], v0 offset:0x3800
	s_waitcnt lgkmcnt(0)
	v_mfma_f32_32x32x16_bf16 v[66:81], v[138:141], v[234:237], v[66:81]
	v_mfma_f32_32x32x16_bf16 v[50:65], v[134:137], v[148:151], v[50:65]
	ds_read_b64_tr_b16 v[148:149], v0 offset:0x200
	ds_read_b64_tr_b16 v[150:151], v0 offset:0xa00
	v_mfma_f32_32x32x16_bf16 v[50:65], v[142:145], v[152:155], v[50:65]
	ds_read_b64_tr_b16 v[152:153], v0 offset:0x1200
	ds_read_b64_tr_b16 v[154:155], v0 offset:0x1a00
	v_mfma_f32_32x32x16_bf16 v[50:65], v[130:133], v[156:159], v[50:65]
	ds_read_b64_tr_b16 v[156:157], v0 offset:0x2200
	ds_read_b64_tr_b16 v[158:159], v0 offset:0x2a00
	ds_read_b64_tr_b16 v[234:235], v0 offset:0x3200
	ds_read_b64_tr_b16 v[236:237], v0 offset:0x3a00
	s_waitcnt lgkmcnt(0)
	v_mfma_f32_32x32x16_bf16 v[50:65], v[138:141], v[230:233], v[50:65]
	v_mfma_f32_32x32x16_bf16 v[34:49], v[134:137], v[148:151], v[34:49]
	ds_read_b64_tr_b16 v[148:149], v0 offset:0x400
	ds_read_b64_tr_b16 v[150:151], v0 offset:0xc00
	v_mfma_f32_32x32x16_bf16 v[34:49], v[142:145], v[152:155], v[34:49]
	ds_read_b64_tr_b16 v[152:153], v0 offset:0x1400
	ds_read_b64_tr_b16 v[154:155], v0 offset:0x1c00
	v_mfma_f32_32x32x16_bf16 v[34:49], v[130:133], v[156:159], v[34:49]
	ds_read_b64_tr_b16 v[156:157], v0 offset:0x2400
	ds_read_b64_tr_b16 v[158:159], v0 offset:0x2c00
	ds_read_b64_tr_b16 v[230:231], v0 offset:0x3400
	ds_read_b64_tr_b16 v[232:233], v0 offset:0x3c00
	s_waitcnt lgkmcnt(0)
	v_mfma_f32_32x32x16_bf16 v[34:49], v[138:141], v[234:237], v[34:49]
	v_mfma_f32_32x32x16_bf16 v[18:33], v[134:137], v[148:151], v[18:33]
	ds_read_b64_tr_b16 v[148:149], v0 offset:0x600
	ds_read_b64_tr_b16 v[150:151], v0 offset:0xe00
	v_mfma_f32_32x32x16_bf16 v[18:33], v[142:145], v[152:155], v[18:33]
	ds_read_b64_tr_b16 v[152:153], v0 offset:0x1600
	ds_read_b64_tr_b16 v[154:155], v0 offset:0x1e00
	v_mfma_f32_32x32x16_bf16 v[18:33], v[130:133], v[156:159], v[18:33]
	ds_read_b64_tr_b16 v[156:157], v0 offset:0x2600
	ds_read_b64_tr_b16 v[158:159], v0 offset:0x2e00
	ds_read_b64_tr_b16 v[234:235], v0 offset:0x3600
	ds_read_b64_tr_b16 v[236:237], v0 offset:0x3e00
	s_waitcnt lgkmcnt(0)
	v_mfma_f32_32x32x16_bf16 v[18:33], v[138:141], v[230:233], v[18:33]
	v_mfma_f32_32x32x16_bf16 v[2:17], v[134:137], v[148:151], v[2:17]
	s_mov_b32 s98, s100
	s_mov_b32 s100, s101
	s_add_i32 s101, s101, 1
	s_cmp_eq_u32 s101, 3
	s_cselect_b32 s101, 0, s101
	s_mov_b64 s[0:1], 0x8000
	v_lshl_add_u64 v[202:203], v[202:203], 0, s[0:1]
	v_lshl_add_u64 v[204:205], v[204:205], 0, s[64:65]
	v_lshl_add_u64 v[206:207], v[206:207], 0, s[64:65]
	s_waitcnt vmcnt(4) lgkmcnt(0)
	s_barrier
	v_mfma_f32_32x32x16_bf16 v[2:17], v[142:145], v[152:155], v[2:17]
	s_cmpk_eq_i32 s68, 0x100
	v_mfma_f32_32x32x16_bf16 v[2:17], v[130:133], v[156:159], v[2:17]
	v_mfma_f32_32x32x16_bf16 v[2:17], v[138:141], v[234:237], v[2:17]
	s_cbranch_scc1 .LBB0_651
	v_mov_b32_e32 v230, v146
	s_branch .LBB0_643
; template <bool WIN>
; __device__ __forceinline__ void partialSM(f32x16& p0, f32x16& p1, float& m_reg, float& mn, float& alpha) {
;   constexpr float C = SCALE * 1.4426950408889634f;
;   float pmax = p0[0];
; #pragma unroll
;   for (int r = 1; r < 16; ++r) pmax = fmaxf(pmax, p0[r]);
; #pragma unroll
;   for (int r = 0; r < 16; ++r) pmax = fmaxf(pmax, p1[r]);
;   { auto rr = __builtin_amdgcn_permlane32_swap(__float_as_uint(pmax), __float_as_uint(pmax), false, false);
;     pmax = fmaxf(__uint_as_float(rr[0]), __uint_as_float(rr[1])); }
;   if (__builtin_expect(__all(pmax - m_reg <= THR / SCALE), 1)) { mn = m_reg; alpha = 1.f; }
;   else { mn = fmaxf(m_reg, pmax); alpha = __builtin_amdgcn_exp2f((m_reg - mn) * C); m_reg = mn; }
;   float mnC = -mn * C;
; #pragma unroll
;   for (int r = 0; r < 16; ++r) p0[r] = fmaf(p0[r], C, mnC);
; #pragma unroll
;   for (int r = 0; r < 16; ++r) p1[r] = fmaf(p1[r], C, mnC);
; template <bool WIN>
; __device__ __forceinline__ void qkt(f32x16& p0, f32x16& p1, const bf16_t* Ks, const bf16x8* qr, int r32, int hi, int dq) {
;   p0 = f32x16{}; p1 = f32x16{};
;   if (WIN) {
;     const int t = 4 * hi - dq + 128;
; #pragma unroll
;     for (int r = 0; r < 16; ++r) { const unsigned d0 = (unsigned)(t + (r & 3) + 8 * (r >> 2)), d1 = d0 + 32u;
;       p0[r] = d0 > 256u ? -1e30f : 0.f; p1[r] = d1 > 256u ? -1e30f : 0.f; }
;   }
; #pragma unroll
;   for (int d0 = 0; d0 < 8; ++d0) { int cb = (d0 * 16 + hi * 8) * 2;
;     bf16x8 b0 = *reinterpret_cast<const bf16x8*>((const char*)Ks + KSWZ(r32, cb));
;     bf16x8 b1 = *reinterpret_cast<const bf16x8*>((const char*)Ks + KSWZ(32 + r32, cb));
;     p0 = __builtin_amdgcn_mfma_f32_32x32x16_bf16(b0, qr[d0], p0, 0, 0, 0);
;     p1 = __builtin_amdgcn_mfma_f32_32x32x16_bf16(b1, qr[d0], p1, 0, 0, 0); }
.Lpl_top:
	s_and_b32 s69, s68, 1
	s_setprio 1
	s_lshl_b32 s0, s69, 14
	s_add_i32 s0, s0, 0
	v_add3_u32 v0, s0, v209, v199
	ds_read_b128 v[130:133], v0
	ds_read_b128 v[134:137], v0 offset:8192
	v_add3_u32 v0, s0, v210, v199
	ds_read_b128 v[232:235], v0
	ds_read_b128 v[236:239], v0 offset:8192
	v_add3_u32 v0, s0, v211, v199
	ds_read_b128 v[246:249], v0
	ds_read_b128 v[250:253], v0 offset:8192
	s_waitcnt lgkmcnt(4)
	v_mfma_f32_32x32x16_bf16 v[146:161], v[130:133], v[162:165], 0
	v_mfma_f32_32x32x16_bf16 v[130:145], v[134:137], v[162:165], 0
	s_waitcnt lgkmcnt(2)
	v_mfma_f32_32x32x16_bf16 v[146:161], v[232:235], v[166:169], v[146:161]
	v_mfma_f32_32x32x16_bf16 v[130:145], v[236:239], v[166:169], v[130:145]
	v_add3_u32 v0, s0, v212, v199
	ds_read_b128 v[232:235], v0
	ds_read_b128 v[236:239], v0 offset:8192
	s_waitcnt lgkmcnt(2)
	v_mfma_f32_32x32x16_bf16 v[146:161], v[246:249], v[170:173], v[146:161]
	v_mfma_f32_32x32x16_bf16 v[130:145], v[250:253], v[170:173], v[130:145]
	v_add3_u32 v0, s0, v213, v199
	ds_read_b128 v[246:249], v0
	ds_read_b128 v[250:253], v0 offset:8192
	s_waitcnt lgkmcnt(2)
	v_mfma_f32_32x32x16_bf16 v[146:161], v[232:235], v[174:177], v[146:161]
	v_mfma_f32_32x32x16_bf16 v[130:145], v[236:239], v[174:177], v[130:145]
	v_add3_u32 v0, s0, v214, v199
	ds_read_b128 v[232:235], v0
	ds_read_b128 v[236:239], v0 offset:8192
	s_waitcnt lgkmcnt(2)
	v_mfma_f32_32x32x16_bf16 v[146:161], v[246:249], v[178:181], v[146:161]
	v_mfma_f32_32x32x16_bf16 v[130:145], v[250:253], v[178:181], v[130:145]
	v_add3_u32 v0, s0, v215, v199
	ds_read_b128 v[246:249], v0
	ds_read_b128 v[250:253], v0 offset:8192
	s_waitcnt lgkmcnt(2)
	v_mfma_f32_32x32x16_bf16 v[146:161], v[232:235], v[182:185], v[146:161]
	v_mfma_f32_32x32x16_bf16 v[130:145], v[236:239], v[182:185], v[130:145]
	v_add3_u32 v0, s0, v216, v199
	ds_read_b128 v[232:235], v0
	ds_read_b128 v[236:239], v0 offset:8192
	s_waitcnt lgkmcnt(2)
	v_mfma_f32_32x32x16_bf16 v[146:161], v[246:249], v[186:189], v[146:161]
	v_mfma_f32_32x32x16_bf16 v[130:145], v[250:253], v[186:189], v[130:145]
	s_waitcnt lgkmcnt(0)
	v_mfma_f32_32x32x16_bf16 v[146:161], v[232:235], v[190:193], v[146:161]
	v_mfma_f32_32x32x16_bf16 v[130:145], v[236:239], v[190:193], v[130:145]
	s_setprio 0
	s_nop 7
	s_nop 3
	v_max_f32_e32 v0, v146, v147
	v_max3_f32 v0, v0, v148, v149
	v_max3_f32 v0, v0, v150, v151
	v_max3_f32 v0, v0, v152, v153
	v_max3_f32 v0, v0, v154, v155
	v_max3_f32 v0, v0, v156, v157
	v_max3_f32 v0, v0, v158, v159
	v_max3_f32 v0, v0, v160, v161
	v_max3_f32 v0, v0, v130, v131
	v_max3_f32 v0, v0, v132, v133
	v_max3_f32 v0, v0, v134, v135
	v_max3_f32 v0, v0, v136, v137
	v_max3_f32 v0, v0, v138, v139
	v_max3_f32 v0, v0, v140, v141
	v_max3_f32 v0, v0, v142, v143
	v_max3_f32 v0, v0, v144, v145
	v_mov_b32_e32 v231, v0
	s_nop 1
	v_permlane32_swap_b32_e32 v0, v231
	v_max_f32_e32 v0, v0, v231
	v_sub_f32_e32 v231, v0, v229
	s_mov_b32 s0, 0x42b504f3
	v_cmp_ge_f32_e32 vcc, s0, v231
	v_max_f32_e32 v232, v229, v229
	s_cmp_eq_u64 vcc, exec
	v_max_f32_e32 v232, v232, v0
	s_cselect_b64 vcc, -1, 0
	v_sub_f32_e32 v0, v229, v232
	v_cndmask_b32_e32 v229, v232, v229, vcc
	v_mul_f32_e32 v231, 0xbe0293ee, v229
	v_fmamk_f32 v146, v146, 0x3e0293ee, v231
	v_fmamk_f32 v147, v147, 0x3e0293ee, v231
	v_fmamk_f32 v148, v148, 0x3e0293ee, v231
	v_fmamk_f32 v149, v149, 0x3e0293ee, v231
	v_fmamk_f32 v150, v150, 0x3e0293ee, v231
	v_fmamk_f32 v151, v151, 0x3e0293ee, v231
	v_fmamk_f32 v152, v152, 0x3e0293ee, v231
	v_fmamk_f32 v153, v153, 0x3e0293ee, v231
	v_fmamk_f32 v154, v154, 0x3e0293ee, v231
	v_fmamk_f32 v155, v155, 0x3e0293ee, v231
	v_fmamk_f32 v156, v156, 0x3e0293ee, v231
	v_fmamk_f32 v157, v157, 0x3e0293ee, v231
	v_fmamk_f32 v158, v158, 0x3e0293ee, v231
	v_fmamk_f32 v159, v159, 0x3e0293ee, v231
	v_fmamk_f32 v160, v160, 0x3e0293ee, v231
	v_fmamk_f32 v161, v161, 0x3e0293ee, v231
	v_fmamk_f32 v130, v130, 0x3e0293ee, v231
	v_fmamk_f32 v131, v131, 0x3e0293ee, v231
	v_fmamk_f32 v132, v132, 0x3e0293ee, v231
	v_fmamk_f32 v133, v133, 0x3e0293ee, v231
	v_fmamk_f32 v134, v134, 0x3e0293ee, v231
	v_fmamk_f32 v135, v135, 0x3e0293ee, v231
	v_fmamk_f32 v136, v136, 0x3e0293ee, v231
	v_fmamk_f32 v137, v137, 0x3e0293ee, v231
	v_fmamk_f32 v138, v138, 0x3e0293ee, v231
	v_fmamk_f32 v139, v139, 0x3e0293ee, v231
	v_fmamk_f32 v140, v140, 0x3e0293ee, v231
	v_fmamk_f32 v141, v141, 0x3e0293ee, v231
	v_fmamk_f32 v142, v142, 0x3e0293ee, v231
	v_fmamk_f32 v143, v143, 0x3e0293ee, v231
	v_fmamk_f32 v144, v144, 0x3e0293ee, v231
	v_fmac_f32_e32 v231, 0x3e0293ee, v145
	v_exp_f32_e32 v145, v146
	v_exp_f32_e32 v146, v147
	v_exp_f32_e32 v147, v148
	v_exp_f32_e32 v148, v149
	v_exp_f32_e32 v149, v150
	v_exp_f32_e32 v150, v151
	v_exp_f32_e32 v151, v152
	v_exp_f32_e32 v152, v153
	v_exp_f32_e32 v153, v154
	v_exp_f32_e32 v154, v155
	v_exp_f32_e32 v155, v156
	v_exp_f32_e32 v156, v157
	v_exp_f32_e32 v157, v158
	v_exp_f32_e32 v158, v159
	v_exp_f32_e32 v159, v160
	v_exp_f32_e32 v160, v161
	v_exp_f32_e32 v161, v134
	v_add_f32_e32 v134, v146, v145
	v_add_f32_e32 v134, v147, v134
	v_add_f32_e32 v134, v148, v134
	v_add_f32_e32 v134, v149, v134
	v_add_f32_e32 v134, v150, v134
	v_add_f32_e32 v134, v151, v134
	v_add_f32_e32 v134, v152, v134
	v_add_f32_e32 v134, v153, v134
	v_add_f32_e32 v134, v154, v134
	v_add_f32_e32 v134, v155, v134
	v_add_f32_e32 v134, v156, v134
	v_exp_f32_e32 v130, v130
	v_add_f32_e32 v134, v157, v134
	v_exp_f32_e32 v131, v131
	v_add_f32_e32 v134, v158, v134
	v_exp_f32_e32 v132, v132
	v_add_f32_e32 v134, v159, v134
	v_exp_f32_e32 v133, v133
	v_add_f32_e32 v134, v160, v134
	v_add_f32_e32 v134, v130, v134
	v_exp_f32_e32 v233, v135
	v_add_f32_e32 v134, v131, v134
	v_exp_f32_e32 v234, v136
; __device__ __forceinline__ void finishSM(f32x16& p0, f32x16& p1, float alpha, float& l_reg, bf16x8& pa0, bf16x8& pa1, bf16x8& pa2, bf16x8& pa3) {
; #pragma unroll
;   for (int r = 0; r < 16; ++r) p1[r] = __builtin_amdgcn_exp2f(p1[r]);
;   float ps = 0;
; #pragma unroll
;   for (int r = 0; r < 16; ++r) ps += p0[r];
; #pragma unroll
;   for (int r = 0; r < 16; ++r) ps += p1[r];
;   { auto rr = __builtin_amdgcn_permlane32_swap(__float_as_uint(ps), __float_as_uint(ps), false, false);
;     ps = __uint_as_float(rr[0]) + __uint_as_float(rr[1]); }
;   l_reg = l_reg * alpha + ps;
;     ...
;   PK4(p0, 0, pa0); PK4(p0, 8, pa1); PK4(p1, 0, pa2); PK4(p1, 8, pa3);
	v_add_f32_e32 v134, v132, v134
	v_exp_f32_e32 v235, v137
	v_add_f32_e32 v134, v133, v134
	v_exp_f32_e32 v138, v138
	v_add_f32_e32 v134, v161, v134
	v_exp_f32_e32 v139, v139
	v_add_f32_e32 v134, v233, v134
	v_exp_f32_e32 v140, v140
	v_add_f32_e32 v134, v234, v134
	v_exp_f32_e32 v141, v141
	v_add_f32_e32 v134, v235, v134
	v_exp_f32_e32 v236, v142
	v_add_f32_e32 v134, v138, v134
	v_exp_f32_e32 v237, v143
	v_add_f32_e32 v134, v139, v134
	v_exp_f32_e32 v238, v144
	v_add_f32_e32 v134, v140, v134
	v_mul_f32_e32 v0, 0x3e0293ee, v0
	v_exp_f32_e32 v239, v231
	v_add_f32_e32 v134, v141, v134
	v_exp_f32_e32 v0, v0
	v_add_f32_e32 v134, v236, v134
	v_add_f32_e32 v134, v237, v134
	v_add_f32_e32 v134, v238, v134
	v_add_f32_e32 v231, v239, v134
	v_cndmask_b32_e64 v0, v0, 1.0, vcc
	v_mov_b32_e32 v232, v231
	v_cvt_pk_bf16_f32 v134, v145, v146
	v_cvt_pk_bf16_f32 v135, v147, v148
	v_cvt_pk_bf16_f32 v136, v149, v150
	v_cvt_pk_bf16_f32 v137, v151, v152
	v_cvt_pk_bf16_f32 v142, v153, v154
	v_cvt_pk_bf16_f32 v143, v155, v156
	v_cvt_pk_bf16_f32 v144, v157, v158
	v_cvt_pk_bf16_f32 v145, v159, v160
	v_cvt_pk_bf16_f32 v130, v130, v131
	v_cvt_pk_bf16_f32 v131, v132, v133
	v_cvt_pk_bf16_f32 v132, v161, v233
	v_cvt_pk_bf16_f32 v133, v234, v235
	v_cvt_pk_bf16_f32 v138, v138, v139
	v_cvt_pk_bf16_f32 v139, v140, v141
	v_cvt_pk_bf16_f32 v140, v236, v237
	v_cvt_pk_bf16_f32 v141, v238, v239
	v_permlane32_swap_b32_e32 v231, v232
	v_permlane32_swap_b32_e32 v134, v136
	v_permlane32_swap_b32_e32 v135, v137
	v_permlane32_swap_b32_e32 v142, v144
	v_permlane32_swap_b32_e32 v143, v145
	v_permlane32_swap_b32_e32 v130, v132
	v_permlane32_swap_b32_e32 v131, v133
	v_permlane32_swap_b32_e32 v138, v140
	v_permlane32_swap_b32_e32 v139, v141
	v_cmp_gt_f32_e32 vcc, 1.0, v0
	s_cbranch_vccz .Lpl_649
	s_and_saveexec_b64 s[0:1], s[6:7]
	ds_write_b32 v228, v0 offset:128
	s_or_b64 exec, exec, s[0:1]
	s_waitcnt lgkmcnt(0)
	v_add_u32_e32 v146, s67, v223
	ds_read_b128 v[158:161], v146 offset:224
	ds_read_b128 v[154:157], v146 offset:192
	ds_read_b128 v[150:153], v146 offset:160
	ds_read_b128 v[146:149], v146 offset:128
	s_waitcnt lgkmcnt(0)
	v_pk_mul_f32 v[126:127], v[126:127], v[158:159]
	v_pk_mul_f32 v[122:123], v[122:123], v[154:155]
	v_pk_mul_f32 v[118:119], v[118:119], v[150:151]
	v_pk_mul_f32 v[128:129], v[128:129], v[160:161]
	v_pk_mul_f32 v[124:125], v[124:125], v[156:157]
	v_pk_mul_f32 v[120:121], v[120:121], v[152:153]
	v_pk_mul_f32 v[116:117], v[116:117], v[148:149]
	v_pk_mul_f32 v[114:115], v[114:115], v[146:147]
	v_pk_mul_f32 v[110:111], v[110:111], v[158:159]
	v_pk_mul_f32 v[106:107], v[106:107], v[154:155]
	v_pk_mul_f32 v[102:103], v[102:103], v[150:151]
	v_pk_mul_f32 v[112:113], v[112:113], v[160:161]
	v_pk_mul_f32 v[108:109], v[108:109], v[156:157]
	v_pk_mul_f32 v[104:105], v[104:105], v[152:153]
	v_pk_mul_f32 v[100:101], v[100:101], v[148:149]
	v_pk_mul_f32 v[98:99], v[98:99], v[146:147]
	v_pk_mul_f32 v[94:95], v[94:95], v[158:159]
	v_pk_mul_f32 v[90:91], v[90:91], v[154:155]
	v_pk_mul_f32 v[86:87], v[86:87], v[150:151]
	v_pk_mul_f32 v[96:97], v[96:97], v[160:161]
	v_pk_mul_f32 v[92:93], v[92:93], v[156:157]
	v_pk_mul_f32 v[88:89], v[88:89], v[152:153]
	v_pk_mul_f32 v[84:85], v[84:85], v[148:149]
	v_pk_mul_f32 v[82:83], v[82:83], v[146:147]
	v_pk_mul_f32 v[78:79], v[78:79], v[158:159]
	v_pk_mul_f32 v[74:75], v[74:75], v[154:155]
	v_pk_mul_f32 v[70:71], v[70:71], v[150:151]
	v_pk_mul_f32 v[80:81], v[80:81], v[160:161]
	v_pk_mul_f32 v[76:77], v[76:77], v[156:157]
	v_pk_mul_f32 v[72:73], v[72:73], v[152:153]
	v_pk_mul_f32 v[68:69], v[68:69], v[148:149]
	v_pk_mul_f32 v[66:67], v[66:67], v[146:147]
	v_pk_mul_f32 v[62:63], v[62:63], v[158:159]
	v_pk_mul_f32 v[58:59], v[58:59], v[154:155]
	v_pk_mul_f32 v[54:55], v[54:55], v[150:151]
	v_pk_mul_f32 v[64:65], v[64:65], v[160:161]
	v_pk_mul_f32 v[60:61], v[60:61], v[156:157]
	v_pk_mul_f32 v[56:57], v[56:57], v[152:153]
	v_pk_mul_f32 v[52:53], v[52:53], v[148:149]
	v_pk_mul_f32 v[50:51], v[50:51], v[146:147]
	v_pk_mul_f32 v[46:47], v[46:47], v[158:159]
	v_pk_mul_f32 v[42:43], v[42:43], v[154:155]
	v_pk_mul_f32 v[38:39], v[38:39], v[150:151]
	v_pk_mul_f32 v[48:49], v[48:49], v[160:161]
	v_pk_mul_f32 v[44:45], v[44:45], v[156:157]
	v_pk_mul_f32 v[40:41], v[40:41], v[152:153]
	v_pk_mul_f32 v[36:37], v[36:37], v[148:149]
	v_pk_mul_f32 v[34:35], v[34:35], v[146:147]
	v_pk_mul_f32 v[30:31], v[30:31], v[158:159]
	v_pk_mul_f32 v[26:27], v[26:27], v[154:155]
	v_pk_mul_f32 v[22:23], v[22:23], v[150:151]
	v_pk_mul_f32 v[32:33], v[32:33], v[160:161]
	v_pk_mul_f32 v[28:29], v[28:29], v[156:157]
	v_pk_mul_f32 v[24:25], v[24:25], v[152:153]
	v_pk_mul_f32 v[20:21], v[20:21], v[148:149]
	v_pk_mul_f32 v[18:19], v[18:19], v[146:147]
	v_pk_mul_f32 v[14:15], v[14:15], v[158:159]
	v_pk_mul_f32 v[10:11], v[10:11], v[154:155]
	v_pk_mul_f32 v[6:7], v[6:7], v[150:151]
	v_pk_mul_f32 v[16:17], v[16:17], v[160:161]
	v_pk_mul_f32 v[12:13], v[12:13], v[156:157]
	v_pk_mul_f32 v[8:9], v[8:9], v[152:153]
	v_pk_mul_f32 v[4:5], v[4:5], v[148:149]
	v_pk_mul_f32 v[2:3], v[2:3], v[146:147]
; #define SBAR() __builtin_amdgcn_sched_barrier(0)
; template <int D0> __device__ __forceinline__ void pv_one(f32x16& od, int vb, bf16x8 pa0, bf16x8 pa1, bf16x8 pa2, bf16x8 pa3) {
;   const s16x4 l0 = tr_read<v_rd_off(D0, 0, 0)>(vb), h0 = tr_read<v_rd_off(D0, 0, 1)>(vb), l1 = tr_read<v_rd_off(D0, 1, 0)>(vb), h1 = tr_read<v_rd_off(D0, 1, 1)>(vb);
;   const s16x4 l2 = tr_read<v_rd_off(D0, 2, 0)>(vb), h2 = tr_read<v_rd_off(D0, 2, 1)>(vb), l3 = tr_read<v_rd_off(D0, 3, 0)>(vb), h3 = tr_read<v_rd_off(D0, 3, 1)>(vb);
;   asm volatile("s_waitcnt lgkmcnt(0)" ::: "memory"); SBAR();
;     ...
;   od = __builtin_amdgcn_mfma_f32_32x32x16_bf16(pa0, PK(l0, h0), od, 0, 0, 0);
;   od = __builtin_amdgcn_mfma_f32_32x32x16_bf16(pa1, PK(l1, h1), od, 0, 0, 0);
;   od = __builtin_amdgcn_mfma_f32_32x32x16_bf16(pa2, PK(l2, h2), od, 0, 0, 0);
;   od = __builtin_amdgcn_mfma_f32_32x32x16_bf16(pa3, PK(l3, h3), od, 0, 0, 0);
;     ...
; }
; __device__ __forceinline__ void pv_d0(f32x16* o, int vb, bf16x8 pa0, bf16x8 pa1, bf16x8 pa2, bf16x8 pa3) {
;   pv_one<0>(o[0], vb, pa0, pa1, pa2, pa3); pv_one<1>(o[1], vb, pa0, pa1, pa2, pa3); pv_one<2>(o[2], vb, pa0, pa1, pa2, pa3); pv_one<3>(o[3], vb, pa0, pa1, pa2, pa3);
; }
; template <int LDO>
; __device__ __forceinline__ void attn_unit_dv(const bf16_t* __restrict__ Qb, const bf16_t* __restrict__ Kh, const bf16_t* __restrict__ Vh, bf16_t* __restrict__ Ob, int NT, char* lds, LAS3 unsigned char* ldsl) {
;     ...
;   if (wid >= 4) __builtin_amdgcn_s_setprio(1);
;   DMA_KV(0, 0);
;   const bf16_t* Qw = Qb + (long)(wid * QBLK + r32) * LDQ + hi * 8;
; #pragma unroll
;   for (int d0 = 0; d0 < 8; ++d0) qr[d0] = ld8(Qw + d0 * 16);
;   const int vb0 = (int)(uintptr_t)(lds + DV_V0) + v_rd_base(lane);
;   asm volatile("s_waitcnt vmcnt(0) lgkmcnt(0)" ::: "memory"); __builtin_amdgcn_s_barrier(); asm volatile("" ::: "memory");
;   for (int t = 0; t < NT; ++t) {
;     const int buf = t & 1;
;     f32x16 p0, p1; float mn, alpha; bf16x8 pa0, pa1, pa2, pa3;
;     qkt<false>(p0, p1, (const bf16_t*)(lds + DV_K0 + buf * 16384), qr, r32, hi, 0);
;     SBAR();
;     if (t + 1 < NT) DMA_KV(t + 1, buf ^ 1);
;     SBAR();
;     partialSM<false>(p0, p1, m_reg, mn, alpha);
;     finishSM(p0, p1, alpha, l_reg, pa0, pa1, pa2, pa3);
;     RESC8(alpha);
;     SBAR();
;     pv_d0(o, vb0 + buf * 32768, pa0, pa1, pa2, pa3);
;     pv_d0(o + 4, vb0 + buf * 32768 + 16384, pa0, pa1, pa2, pa3);
.Lpl_649:
	s_waitcnt vmcnt(4)
	s_barrier
	s_lshl_b32 s0, s69, 14
	s_add_i32 s0, s35, s0
	v_lshl_add_u64 v[254:255], s[22:23], 0, v[206:207]
	v_lshl_add_u64 v[254:255], v[254:255], 0, s[64:65]
	s_mov_b32 m0, s0
	s_nop 0
	global_load_lds_dwordx4 v[254:255], off
	v_lshl_add_u64 v[254:255], s[22:23], 0, v[204:205]
	v_lshl_add_u64 v[254:255], v[254:255], 0, s[64:65]
	s_add_i32 m0, s0, 0x400
	s_nop 0
	global_load_lds_dwordx4 v[254:255], off
	s_lshl_b32 s0, s101, 15
	s_add_i32 s33, s66, s0
	v_lshl_add_u64 v[254:255], s[22:23], 0, v[202:203]
	s_mov_b64 s[0:1], 0x33e10000
	v_lshl_add_u64 v[254:255], v[254:255], 0, s[0:1]
	s_add_i32 m0, s33, 0x8000
	s_mov_b64 s[0:1], 0x80
	global_load_lds_dwordx4 v[254:255], off
	v_lshl_add_u64 v[254:255], v[254:255], 0, s[0:1]
	s_add_i32 m0, s33, 0x8400
	s_mov_b64 s[0:1], 0x780
	global_load_lds_dwordx4 v[254:255], off
	v_lshl_add_u64 v[254:255], v[254:255], 0, s[0:1]
	s_add_i32 m0, s33, 0x8800
	s_mov_b64 s[0:1], 0x80
	global_load_lds_dwordx4 v[254:255], off
	v_lshl_add_u64 v[254:255], v[254:255], 0, s[0:1]
	s_add_i32 m0, s33, 0x8c00
	s_nop 0
	global_load_lds_dwordx4 v[254:255], off
	v_add_f32_e32 v146, v231, v232
	v_fmac_f32_e32 v146, v230, v0
	s_add_i32 s68, s68, 1
	v_lshl_add_u32 v0, s98, 15, v224
	ds_read_b64_tr_b16 v[148:149], v0 offset:0
	ds_read_b64_tr_b16 v[150:151], v0 offset:0x800
	ds_read_b64_tr_b16 v[152:153], v0 offset:0x1000
	ds_read_b64_tr_b16 v[154:155], v0 offset:0x1800
	ds_read_b64_tr_b16 v[156:157], v0 offset:0x2000
	ds_read_b64_tr_b16 v[158:159], v0 offset:0x2800
	ds_read_b64_tr_b16 v[230:231], v0 offset:0x3000
	ds_read_b64_tr_b16 v[232:233], v0 offset:0x3800
	s_waitcnt lgkmcnt(0)
	s_nop 0
	v_mfma_f32_32x32x16_bf16 v[114:129], v[134:137], v[148:151], v[114:129]
	ds_read_b64_tr_b16 v[148:149], v0 offset:0x200
	ds_read_b64_tr_b16 v[150:151], v0 offset:0xa00
	v_mfma_f32_32x32x16_bf16 v[114:129], v[142:145], v[152:155], v[114:129]
	ds_read_b64_tr_b16 v[152:153], v0 offset:0x1200
	ds_read_b64_tr_b16 v[154:155], v0 offset:0x1a00
	v_mfma_f32_32x32x16_bf16 v[114:129], v[130:133], v[156:159], v[114:129]
	ds_read_b64_tr_b16 v[156:157], v0 offset:0x2200
	ds_read_b64_tr_b16 v[158:159], v0 offset:0x2a00
	ds_read_b64_tr_b16 v[234:235], v0 offset:0x3200
	ds_read_b64_tr_b16 v[236:237], v0 offset:0x3a00
	s_waitcnt lgkmcnt(0)
	v_mfma_f32_32x32x16_bf16 v[114:129], v[138:141], v[230:233], v[114:129]
	v_mfma_f32_32x32x16_bf16 v[98:113], v[134:137], v[148:151], v[98:113]
	ds_read_b64_tr_b16 v[148:149], v0 offset:0x400
	ds_read_b64_tr_b16 v[150:151], v0 offset:0xc00
	v_mfma_f32_32x32x16_bf16 v[98:113], v[142:145], v[152:155], v[98:113]
	ds_read_b64_tr_b16 v[152:153], v0 offset:0x1400
	ds_read_b64_tr_b16 v[154:155], v0 offset:0x1c00
	v_mfma_f32_32x32x16_bf16 v[98:113], v[130:133], v[156:159], v[98:113]
	ds_read_b64_tr_b16 v[156:157], v0 offset:0x2400
	ds_read_b64_tr_b16 v[158:159], v0 offset:0x2c00
	ds_read_b64_tr_b16 v[230:231], v0 offset:0x3400
	ds_read_b64_tr_b16 v[232:233], v0 offset:0x3c00
	s_waitcnt lgkmcnt(0)
	v_mfma_f32_32x32x16_bf16 v[98:113], v[138:141], v[234:237], v[98:113]
	v_mfma_f32_32x32x16_bf16 v[82:97], v[134:137], v[148:151], v[82:97]
	ds_read_b64_tr_b16 v[148:149], v0 offset:0x600
	ds_read_b64_tr_b16 v[150:151], v0 offset:0xe00
	v_mfma_f32_32x32x16_bf16 v[82:97], v[142:145], v[152:155], v[82:97]
	ds_read_b64_tr_b16 v[152:153], v0 offset:0x1600
	ds_read_b64_tr_b16 v[154:155], v0 offset:0x1e00
	v_mfma_f32_32x32x16_bf16 v[82:97], v[130:133], v[156:159], v[82:97]
	ds_read_b64_tr_b16 v[156:157], v0 offset:0x2600
	ds_read_b64_tr_b16 v[158:159], v0 offset:0x2e00
	ds_read_b64_tr_b16 v[234:235], v0 offset:0x3600
	ds_read_b64_tr_b16 v[236:237], v0 offset:0x3e00
	s_waitcnt lgkmcnt(0)
	v_mfma_f32_32x32x16_bf16 v[82:97], v[138:141], v[230:233], v[82:97]
	v_mfma_f32_32x32x16_bf16 v[66:81], v[134:137], v[148:151], v[66:81]
	v_add_u32_e32 v0, 0x4000, v0
	ds_read_b64_tr_b16 v[148:149], v0 offset:0
	ds_read_b64_tr_b16 v[150:151], v0 offset:0x800
	v_mfma_f32_32x32x16_bf16 v[66:81], v[142:145], v[152:155], v[66:81]
	ds_read_b64_tr_b16 v[152:153], v0 offset:0x1000
	ds_read_b64_tr_b16 v[154:155], v0 offset:0x1800
	v_mfma_f32_32x32x16_bf16 v[66:81], v[130:133], v[156:159], v[66:81]
	ds_read_b64_tr_b16 v[156:157], v0 offset:0x2000
	ds_read_b64_tr_b16 v[158:159], v0 offset:0x2800
	ds_read_b64_tr_b16 v[230:231], v0 offset:0x3000
	ds_read_b64_tr_b16 v[232:233], v0 offset:0x3800
	s_waitcnt lgkmcnt(0)
	v_mfma_f32_32x32x16_bf16 v[66:81], v[138:141], v[234:237], v[66:81]
	v_mfma_f32_32x32x16_bf16 v[50:65], v[134:137], v[148:151], v[50:65]
	ds_read_b64_tr_b16 v[148:149], v0 offset:0x200
	ds_read_b64_tr_b16 v[150:151], v0 offset:0xa00
	v_mfma_f32_32x32x16_bf16 v[50:65], v[142:145], v[152:155], v[50:65]
	ds_read_b64_tr_b16 v[152:153], v0 offset:0x1200
	ds_read_b64_tr_b16 v[154:155], v0 offset:0x1a00
	v_mfma_f32_32x32x16_bf16 v[50:65], v[130:133], v[156:159], v[50:65]
	ds_read_b64_tr_b16 v[156:157], v0 offset:0x2200
	ds_read_b64_tr_b16 v[158:159], v0 offset:0x2a00
	ds_read_b64_tr_b16 v[234:235], v0 offset:0x3200
	ds_read_b64_tr_b16 v[236:237], v0 offset:0x3a00
	s_waitcnt lgkmcnt(0)
	v_mfma_f32_32x32x16_bf16 v[50:65], v[138:141], v[230:233], v[50:65]
	v_mfma_f32_32x32x16_bf16 v[34:49], v[134:137], v[148:151], v[34:49]
	ds_read_b64_tr_b16 v[148:149], v0 offset:0x400
	ds_read_b64_tr_b16 v[150:151], v0 offset:0xc00
	v_mfma_f32_32x32x16_bf16 v[34:49], v[142:145], v[152:155], v[34:49]
	ds_read_b64_tr_b16 v[152:153], v0 offset:0x1400
	ds_read_b64_tr_b16 v[154:155], v0 offset:0x1c00
	v_mfma_f32_32x32x16_bf16 v[34:49], v[130:133], v[156:159], v[34:49]
	ds_read_b64_tr_b16 v[156:157], v0 offset:0x2400
	ds_read_b64_tr_b16 v[158:159], v0 offset:0x2c00
	ds_read_b64_tr_b16 v[230:231], v0 offset:0x3400
	ds_read_b64_tr_b16 v[232:233], v0 offset:0x3c00
	s_waitcnt lgkmcnt(0)
	v_mfma_f32_32x32x16_bf16 v[34:49], v[138:141], v[234:237], v[34:49]
	v_mfma_f32_32x32x16_bf16 v[18:33], v[134:137], v[148:151], v[18:33]
	ds_read_b64_tr_b16 v[148:149], v0 offset:0x600
	ds_read_b64_tr_b16 v[150:151], v0 offset:0xe00
	v_mfma_f32_32x32x16_bf16 v[18:33], v[142:145], v[152:155], v[18:33]
	ds_read_b64_tr_b16 v[152:153], v0 offset:0x1600
	ds_read_b64_tr_b16 v[154:155], v0 offset:0x1e00
	v_mfma_f32_32x32x16_bf16 v[18:33], v[130:133], v[156:159], v[18:33]
	ds_read_b64_tr_b16 v[156:157], v0 offset:0x2600
	ds_read_b64_tr_b16 v[158:159], v0 offset:0x2e00
	ds_read_b64_tr_b16 v[234:235], v0 offset:0x3600
	ds_read_b64_tr_b16 v[236:237], v0 offset:0x3e00
	s_waitcnt lgkmcnt(0)
	v_mfma_f32_32x32x16_bf16 v[18:33], v[138:141], v[230:233], v[18:33]
	v_mfma_f32_32x32x16_bf16 v[2:17], v[134:137], v[148:151], v[2:17]
	s_mov_b32 s98, s100
	s_mov_b32 s100, s101
	s_add_i32 s101, s101, 1
	s_cmp_eq_u32 s101, 3
	s_cselect_b32 s101, 0, s101
	s_mov_b64 s[0:1], 0x8000
	v_lshl_add_u64 v[202:203], v[202:203], 0, s[0:1]
	v_lshl_add_u64 v[204:205], v[204:205], 0, s[64:65]
	v_lshl_add_u64 v[206:207], v[206:207], 0, s[64:65]
	s_waitcnt vmcnt(6) lgkmcnt(0)
	s_barrier
; template <int LDO>
; __device__ __forceinline__ void attn_unit_dv(const bf16_t* __restrict__ Qb, const bf16_t* __restrict__ Kh, const bf16_t* __restrict__ Vh, bf16_t* __restrict__ Ob, int NT, char* lds, LAS3 unsigned char* ldsl) {
;     ...
;     pv_d0(o, vb0 + buf * 32768, pa0, pa1, pa2, pa3);
;     pv_d0(o + 4, vb0 + buf * 32768 + 16384, pa0, pa1, pa2, pa3);
;     asm volatile("s_waitcnt vmcnt(0) lgkmcnt(0)" ::: "memory"); __builtin_amdgcn_s_barrier(); asm volatile("" ::: "memory");
	v_mfma_f32_32x32x16_bf16 v[2:17], v[142:145], v[152:155], v[2:17]
	s_cmpk_eq_i32 s68, 0x100
	v_mfma_f32_32x32x16_bf16 v[2:17], v[130:133], v[156:159], v[2:17]
	v_mfma_f32_32x32x16_bf16 v[2:17], v[138:141], v[234:237], v[2:17]
	s_cbranch_scc1 .LBB0_651
	v_mov_b32_e32 v230, v146
	s_branch .Lpl_top
